# attention: coalesced K/V tile staging loads (8 rows x 128 B per wave instead of 64 rows x 16 B)
# baseline (speedup 1.0000x reference)
;     ...
;     const int lkey = lane, lch = wid;
;     const int kk = lkey & 31, slot = (lkey & 32) | (8 * ((kk >> 2) & 3) + 4 * (kk >> 4) + (kk & 3));
;     const bf16* kg = Kb + (rowbase + lkey) * 1024 + h * HD + lch * 8;
;     const bf16* vg = Vb + (rowbase + lkey) * 1024 + h * HD + lch * 8;
;     u32x4 kreg, vreg;
;     kreg = *(const u32x4*)(kg + (size_t)(NT - 1) * 64 * 1024); vreg = *(const u32x4*)(vg + (size_t)(NT - 1) * 64 * 1024);
;     ...
;     AT_WRITE(0);
;     __syncthreads();
.LBB0_457:
	s_xor_b64 s[28:29], s[4:5], -1
	s_and_b64 s[4:5], s[4:5], exec
	v_readlane_b32 s1, v255, 48
	v_mov_b32_e32 v104, v232
	s_cselect_b32 s6, s1, s0
	v_readlane_b32 s12, v254, 58
	v_readfirstlane_b32 s1, v104
	s_ashr_i32 s33, s1, 6
	s_lshl_b32 s1, s6, 8
	s_lshl_b32 s24, s33, 5
	s_add_i32 s24, s24, s1
	s_ashr_i32 s4, s24, 31
	s_add_u32 s10, s18, s24
	v_and_b32_e32 v106, 31, v104
	s_addc_u32 s11, s19, s4
	v_or_b32_e32 v0, s10, v106
	v_mov_b32_e32 v1, s11
	v_bfe_u32 v4, v104, 5, 1
	v_lshlrev_b64 v[0:1], 12, v[0:1]
	v_lshl_add_u64 v[0:1], s[30:31], 0, v[0:1]
	v_lshlrev_b32_e32 v64, 4, v4
	v_lshl_add_u64 v[0:1], v[0:1], 0, v[64:65]
	global_load_dwordx4 v[66:69], v[0:1], off offset:2048
	global_load_dwordx4 v[70:73], v[0:1], off offset:2080
	global_load_dwordx4 v[74:77], v[0:1], off offset:2112
	global_load_dwordx4 v[78:81], v[0:1], off offset:2144
	v_bfe_u32 v114, v104, 3, 3
	v_and_b32_e32 v115, 7, v104
	v_lshl_or_b32 v114, s33, 3, v114
	v_and_b32_e32 v105, 63, v104
	v_lshlrev_b32_e32 v0, 1, v114
	v_lshrrev_b32_e32 v1, 2, v114
	v_and_b32_e32 v0, 24, v0
	v_and_b32_e32 v1, 4, v1
	v_and_b32_e32 v2, 35, v114
	v_or3_b32 v5, v2, v1, v0
	v_or_b32_e32 v0, s18, v114
	v_mov_b32_e32 v1, s19
	v_readlane_b32 s4, v255, 49
	v_lshlrev_b64 v[0:1], 11, v[0:1]
	v_readlane_b32 s5, v255, 50
	s_lshl_b32 s7, s6, 19
	v_readlane_b32 s13, v254, 59
	v_lshl_or_b32 v0, v115, 4, v0
	v_lshl_add_u64 v[2:3], s[4:5], 0, v[0:1]
	s_mov_b32 s4, 0
	s_ashr_i32 s5, s4, 31
	s_lshl_b64 s[4:5], s[4:5], 1
	v_lshl_add_u64 v[0:1], s[8:9], 0, v[0:1]
	v_lshl_add_u64 v[2:3], v[2:3], 0, s[4:5]
	v_lshl_add_u64 v[0:1], v[0:1], 0, s[4:5]
	s_mov_b32 s21, s13
	s_or_b32 s20, s7, 0x60000
	v_lshl_add_u64 v[2:3], v[2:3], 0, s[20:21]
	v_lshl_add_u64 v[0:1], v[0:1], 0, s[20:21]
	global_load_dwordx4 v[82:85], v[2:3], off
	global_load_dwordx4 v[86:89], v[0:1], off
	s_lshl_b32 s25, s6, 2
	s_lshl_b32 s6, s33, 10
	v_writelane_b32 v254, s12, 58
	s_add_i32 s20, s6, 0
	s_mul_i32 s6, s33, 0x480
	v_writelane_b32 v254, s13, 59
	s_add_i32 s6, s6, 0
	v_mul_u32_u24_e32 v108, 0x480, v115
	v_lshl_add_u32 v108, v114, 1, v108
	s_lshl_b32 s6, s33, 2
	v_readlane_b32 s12, v254, 57
	s_add_i32 s25, s25, 4
	s_add_i32 s26, s12, s6
	v_lshlrev_b32_e32 v0, 10, v4
	v_lshlrev_b32_e32 v1, 4, v106
	v_add3_u32 v111, 0, v0, v1
	v_mul_u32_u24_e32 v0, 0x90, v106
	v_and_b32_e32 v1, 32, v104
	s_add_u32 s4, s4, s7
	v_add3_u32 v112, 0, v0, v1
	v_lshlrev_b32_e32 v0, 11, v114
	v_mov_b32_e32 v1, v65
	s_addc_u32 s5, s5, 0
	v_lshl_or_b32 v0, v115, 4, v0
	v_lshl_add_u64 v[0:1], s[4:5], 0, v[0:1]
	v_mov_b32_e32 v14, v65
	v_mov_b32_e32 v15, v65
	v_lshlrev_b32_e32 v107, 4, v5
	v_lshl_or_b32 v107, v115, 10, v107
	v_lshl_add_u64 v[90:91], s[34:35], 0, v[0:1]
	v_lshl_add_u64 v[92:93], s[2:3], 0, v[0:1]
	v_mov_b32_e32 v0, v65
	v_mov_b32_e32 v1, v65
	v_mov_b32_e32 v2, v65
	v_mov_b32_e32 v3, v65
	v_mov_b32_e32 v4, v65
	v_mov_b32_e32 v5, v65
	v_mov_b32_e32 v6, v65
	v_mov_b32_e32 v7, v65
	v_mov_b32_e32 v8, v65
	v_mov_b32_e32 v9, v65
	v_mov_b32_e32 v10, v65
	v_mov_b32_e32 v11, v65
	v_mov_b32_e32 v12, v65
	v_mov_b32_e32 v13, v65
	v_mov_b64_e32 v[30:31], v[14:15]
	v_or_b32_e32 v109, s24, v106
	v_lshl_add_u32 v110, v105, 2, s12
	v_cmp_gt_u32_e64 s[36:37], 32, v105
	s_mov_b32 s6, 0
	v_cmp_eq_u32_e64 s[38:39], 0, v105
	v_cmp_gt_u32_e64 s[40:41], 8, v105
	s_or_b32 s27, s1, 0xc0
	v_mov_b32_e32 v95, 1.0
	v_mov_b32_e32 v32, 1
	v_mov_b64_e32 v[28:29], v[12:13]
	v_mov_b64_e32 v[26:27], v[10:11]
	v_mov_b64_e32 v[24:25], v[8:9]
	v_mov_b64_e32 v[22:23], v[6:7]
	v_mov_b64_e32 v[20:21], v[4:5]
	v_mov_b64_e32 v[18:19], v[2:3]
	v_mov_b64_e32 v[16:17], v[0:1]
	s_waitcnt vmcnt(1)
	ds_write_b128 v107, v[82:85]
	s_waitcnt vmcnt(0)
	ds_write_b16 v108, v86 offset:16384
	ds_write_b16_d16_hi v108, v86 offset:16528
	ds_write_b16 v108, v87 offset:16672
	ds_write_b16_d16_hi v108, v87 offset:16816
	ds_write_b16 v108, v88 offset:16960
	ds_write_b16_d16_hi v108, v88 offset:17104
	ds_write_b16 v108, v89 offset:17248
	ds_write_b16_d16_hi v108, v89 offset:17392
	s_waitcnt lgkmcnt(0)
	s_barrier
	s_cmpk_eq_i32 s27, 0xffc0
	s_cbranch_scc0 .LBB0_459
